# weight-conversion item order changed to k-block-fastest so concurrent waves write whole bf16 rows (G1/G3/G5 copies), on top of previous stack
# baseline (speedup 1.0000x reference)
.LBB0_336:
	s_lshr_b32 s10, s6, 6
	v_cvt_f32_u32_e32 v2, s10
	s_sub_i32 s17, 0, s10
	s_abs_i32 s16, s39
	s_ashr_i32 s11, s39, 31
	v_rcp_iflag_f32_e32 v2, v2
	s_nop 0
	v_mul_f32_e32 v2, 0x4f7ffffe, v2
	v_cvt_u32_f32_e32 v2, v2
	s_nop 0
	v_readfirstlane_b32 s37, v2
	s_mul_i32 s17, s17, s37
	s_mul_hi_u32 s17, s37, s17
	s_add_i32 s37, s37, s17
	s_mul_hi_u32 s17, s16, s37
	s_mul_i32 s37, s17, s10
	s_sub_i32 s16, s16, s37
	s_add_i32 s37, s17, 1
	s_sub_i32 s38, s16, s10
	s_cmp_ge_u32 s16, s10
	s_cselect_b32 s17, s37, s17
	s_cselect_b32 s16, s38, s16
	s_add_i32 s37, s17, 1
	s_cmp_ge_u32 s16, s10
	s_cselect_b32 s16, s37, s17
	s_xor_b32 s16, s16, s11
	s_sub_i32 s11, s16, s11
	s_mul_i32 s10, s11, s10
	s_sub_i32 s10, s39, s10
	s_mov_b32 s37, s11
	s_lshl_b32 s16, s10, 6
	v_or_b32_e32 v2, s16, v10
	s_ashr_i32 s17, s16, 31
	s_mul_i32 s11, s17, s45
	v_mad_u64_u32 v[2:3], s[38:39], v2, s45, 0
	s_lshl_b32 s10, s37, 5
	v_add_u32_e32 v3, s11, v3
	v_lshl_add_u64 v[2:3], v[2:3], 2, s[14:15]
	s_ashr_i32 s11, s10, 31
	v_lshl_add_u64 v[2:3], s[10:11], 2, v[2:3]
	v_lshl_add_u64 v[8:9], v[2:3], 0, v[0:1]
	s_lshl_b32 s14, s45, 3
	s_mov_b32 s15, s50
	global_load_dwordx4 v[2:5], v[8:9], off nt
	v_lshl_add_u64 v[20:21], s[14:15], 2, v[8:9]
	global_load_dwordx4 v[20:23], v[20:21], off nt
	s_lshl_b32 s14, s45, 4
	v_lshl_add_u64 v[24:25], s[14:15], 2, v[8:9]
	global_load_dwordx4 v[24:27], v[24:25], off nt
	s_mul_i32 s14, s45, 24
	v_lshl_add_u64 v[28:29], s[14:15], 2, v[8:9]
	global_load_dwordx4 v[28:31], v[28:29], off nt
	s_lshl_b32 s14, s45, 5
	v_lshl_add_u64 v[32:33], s[14:15], 2, v[8:9]
	global_load_dwordx4 v[32:35], v[32:33], off nt
	s_mul_i32 s14, s45, 40
	v_lshl_add_u64 v[36:37], s[14:15], 2, v[8:9]
	global_load_dwordx4 v[36:39], v[36:37], off nt
	s_mul_i32 s14, s45, 48
	v_lshl_add_u64 v[40:41], s[14:15], 2, v[8:9]
	global_load_dwordx4 v[40:43], v[40:41], off nt
	s_mul_i32 s14, s45, 56
	v_lshl_add_u64 v[8:9], s[14:15], 2, v[8:9]
	global_load_dwordx4 v[44:47], v[8:9], off nt
	v_writelane_b32 v255, s6, 40
	v_writelane_b32 v255, s7, 41
	v_writelane_b32 v255, s8, 42
	v_writelane_b32 v255, s9, 43
	v_writelane_b32 v255, s10, 44
	v_writelane_b32 v255, s11, 45
	v_writelane_b32 v255, s14, 46
	v_writelane_b32 v255, s15, 47
	v_writelane_b32 v255, s16, 48
	v_writelane_b32 v255, s17, 49
	v_writelane_b32 v255, s36, 50
	v_writelane_b32 v255, s37, 51
	v_writelane_b32 v255, s48, 52
	s_cmp_eq_u32 s99, 1
	s_cbranch_scc1 .Lcv_tail_G5

.LBB0_704:
	s_lshr_b32 s8, s4, 6
	v_cvt_f32_u32_e32 v2, s8
	s_sub_i32 s15, 0, s8
	s_abs_i32 s14, s37
	s_ashr_i32 s9, s37, 31
	v_rcp_iflag_f32_e32 v2, v2
	s_nop 0
	v_mul_f32_e32 v2, 0x4f7ffffe, v2
	v_cvt_u32_f32_e32 v2, v2
	s_nop 0
	v_readfirstlane_b32 s35, v2
	s_mul_i32 s15, s15, s35
	s_mul_hi_u32 s15, s35, s15
	s_add_i32 s35, s35, s15
	s_mul_hi_u32 s15, s14, s35
	s_mul_i32 s35, s15, s8
	s_sub_i32 s14, s14, s35
	s_add_i32 s35, s15, 1
	s_sub_i32 s36, s14, s8
	s_cmp_ge_u32 s14, s8
	s_cselect_b32 s15, s35, s15
	s_cselect_b32 s14, s36, s14
	s_add_i32 s35, s15, 1
	s_cmp_ge_u32 s14, s8
	s_cselect_b32 s14, s35, s15
	s_xor_b32 s14, s14, s9
	s_sub_i32 s9, s14, s9
	s_mul_i32 s8, s9, s8
	s_sub_i32 s8, s37, s8
	s_mov_b32 s35, s9
	s_lshl_b32 s14, s8, 6
	v_or_b32_e32 v2, s14, v10
	s_ashr_i32 s15, s14, 31
	s_mul_i32 s9, s15, s39
	v_mad_u64_u32 v[2:3], s[36:37], v2, s39, 0
	s_lshl_b32 s8, s35, 5
	v_add_u32_e32 v3, s9, v3
	s_waitcnt lgkmcnt(0)
	v_lshl_add_u64 v[2:3], v[2:3], 2, s[10:11]
	s_ashr_i32 s9, s8, 31
	v_lshl_add_u64 v[2:3], s[8:9], 2, v[2:3]
	v_lshl_add_u64 v[8:9], v[2:3], 0, v[0:1]
	s_lshl_b32 s10, s39, 3
	s_mov_b32 s11, s50
	global_load_dwordx4 v[2:5], v[8:9], off nt
	v_lshl_add_u64 v[20:21], s[10:11], 2, v[8:9]
	global_load_dwordx4 v[20:23], v[20:21], off nt
	s_lshl_b32 s10, s39, 4
	v_lshl_add_u64 v[24:25], s[10:11], 2, v[8:9]
	global_load_dwordx4 v[24:27], v[24:25], off nt
	s_mul_i32 s10, s39, 24
	v_lshl_add_u64 v[28:29], s[10:11], 2, v[8:9]
	global_load_dwordx4 v[28:31], v[28:29], off nt
	s_lshl_b32 s10, s39, 5
	v_lshl_add_u64 v[32:33], s[10:11], 2, v[8:9]
	global_load_dwordx4 v[32:35], v[32:33], off nt
	s_mul_i32 s10, s39, 40
	v_lshl_add_u64 v[36:37], s[10:11], 2, v[8:9]
	global_load_dwordx4 v[36:39], v[36:37], off nt
	s_mul_i32 s10, s39, 48
	v_lshl_add_u64 v[40:41], s[10:11], 2, v[8:9]
	global_load_dwordx4 v[40:43], v[40:41], off nt
	s_mul_i32 s10, s39, 56
	v_lshl_add_u64 v[8:9], s[10:11], 2, v[8:9]
	global_load_dwordx4 v[44:47], v[8:9], off nt
	v_writelane_b32 v255, s4, 40
	v_writelane_b32 v255, s5, 41
	v_writelane_b32 v255, s6, 42
	v_writelane_b32 v255, s7, 43
	v_writelane_b32 v255, s8, 44
	v_writelane_b32 v255, s9, 45
	v_writelane_b32 v255, s10, 46
	v_writelane_b32 v255, s11, 47
	v_writelane_b32 v255, s14, 48
	v_writelane_b32 v255, s15, 49
	v_writelane_b32 v255, s34, 50
	v_writelane_b32 v255, s35, 51
	v_writelane_b32 v255, s44, 52
	s_cmp_eq_u32 s99, 1
	s_cbranch_scc1 .Lcv_tail_G1

.LBB0_1104:
	s_lshr_b32 s8, s4, 6
	v_cvt_f32_u32_e32 v2, s8
	s_sub_i32 s15, 0, s8
	s_abs_i32 s14, s39
	s_ashr_i32 s9, s39, 31
	v_rcp_iflag_f32_e32 v2, v2
	s_nop 0
	v_mul_f32_e32 v2, 0x4f7ffffe, v2
	v_cvt_u32_f32_e32 v2, v2
	s_nop 0
	v_readfirstlane_b32 s37, v2
	s_mul_i32 s15, s15, s37
	s_mul_hi_u32 s15, s37, s15
	s_add_i32 s37, s37, s15
	s_mul_hi_u32 s15, s14, s37
	s_mul_i32 s37, s15, s8
	s_sub_i32 s14, s14, s37
	s_add_i32 s37, s15, 1
	s_sub_i32 s38, s14, s8
	s_cmp_ge_u32 s14, s8
	s_cselect_b32 s15, s37, s15
	s_cselect_b32 s14, s38, s14
	s_add_i32 s37, s15, 1
	s_cmp_ge_u32 s14, s8
	s_cselect_b32 s14, s37, s15
	s_xor_b32 s14, s14, s9
	s_sub_i32 s9, s14, s9
	s_mul_i32 s8, s9, s8
	s_sub_i32 s8, s39, s8
	s_mov_b32 s37, s9
	s_lshl_b32 s14, s8, 6
	v_or_b32_e32 v2, s14, v10
	s_ashr_i32 s15, s14, 31
	s_mul_i32 s9, s15, s45
	v_mad_u64_u32 v[2:3], s[38:39], v2, s45, 0
	s_lshl_b32 s8, s37, 5
	v_add_u32_e32 v3, s9, v3
	v_lshl_add_u64 v[2:3], v[2:3], 2, s[10:11]
	s_ashr_i32 s9, s8, 31
	v_lshl_add_u64 v[2:3], s[8:9], 2, v[2:3]
	v_lshl_add_u64 v[8:9], v[2:3], 0, v[0:1]
	s_lshl_b32 s10, s45, 3
	s_mov_b32 s11, s50
	global_load_dwordx4 v[2:5], v[8:9], off nt
	v_lshl_add_u64 v[20:21], s[10:11], 2, v[8:9]
	global_load_dwordx4 v[20:23], v[20:21], off nt
	s_lshl_b32 s10, s45, 4
	v_lshl_add_u64 v[24:25], s[10:11], 2, v[8:9]
	global_load_dwordx4 v[24:27], v[24:25], off nt
	s_mul_i32 s10, s45, 24
	v_lshl_add_u64 v[28:29], s[10:11], 2, v[8:9]
	global_load_dwordx4 v[28:31], v[28:29], off nt
	s_lshl_b32 s10, s45, 5
	v_lshl_add_u64 v[32:33], s[10:11], 2, v[8:9]
	global_load_dwordx4 v[32:35], v[32:33], off nt
	s_mul_i32 s10, s45, 40
	v_lshl_add_u64 v[36:37], s[10:11], 2, v[8:9]
	global_load_dwordx4 v[36:39], v[36:37], off nt
	s_mul_i32 s10, s45, 48
	v_lshl_add_u64 v[40:41], s[10:11], 2, v[8:9]
	global_load_dwordx4 v[40:43], v[40:41], off nt
	s_mul_i32 s10, s45, 56
	v_lshl_add_u64 v[8:9], s[10:11], 2, v[8:9]
	global_load_dwordx4 v[44:47], v[8:9], off nt
	v_writelane_b32 v255, s4, 40
	v_writelane_b32 v255, s5, 41
	v_writelane_b32 v255, s6, 42
	v_writelane_b32 v255, s7, 43
	v_writelane_b32 v255, s8, 44
	v_writelane_b32 v255, s9, 45
	v_writelane_b32 v255, s10, 46
	v_writelane_b32 v255, s11, 47
	v_writelane_b32 v255, s14, 48
	v_writelane_b32 v255, s15, 49
	v_writelane_b32 v255, s36, 50
	v_writelane_b32 v255, s37, 51
	v_writelane_b32 v255, s48, 52
	s_cmp_eq_u32 s99, 1
	s_cbranch_scc1 .Lcv_tail_G3
